# P2 static loops: sgu_prep 4th row load hoisted next to the other three; loop-invariant gain loads waited once before the sgu_prep / nsa_prep2 loops instead of vmcnt at every loop top (on top of v15b)
# baseline (speedup 1.0000x reference)
; __device__ __forceinline__ int ltid() { int t = threadIdx.x; asm volatile("" : "+v"(t)); return t; }
; __device__ __forceinline__ void ph_sgu_prep(const bf16* __restrict__ proj, const float* __restrict__ ln_g, const float* __restrict__ ln_b, bf16* __restrict__ VLN) {
;     const int tid = ltid(); const int lane = tid & 63; const int gw = blockIdx.x * NWAVES + (tid >> 6), ngw = gridDim.x * NWAVES;
;     float lg[8], lb[8];
; #pragma unroll
;     for (int j = 0; j < 8; ++j) { lg[j] = ln_g[lane * 8 + j]; lb[j] = ln_b[lane * 8 + j]; }
;     for (int m0 = gw; m0 < M; m0 += 4 * ngw) {
.LBB0_1307:
	s_or_b64 exec, exec, s[54:55]
	v_mov_b32_e32 v1, 22
	s_waitcnt vmcnt(63) expcnt(7) lgkmcnt(15)
	s_barrier
	v_readlane_b32 s4, v254, 35
	v_readlane_b32 s96, v255, 6
	v_readlane_b32 s97, v255, 7
	v_lshl_add_u32 v1, v1, 3, s4
	ds_read_b64 v[4:5], v1
	v_mov_b32_e32 v1, 7
	s_lshl_b32 s64, s96, 9
	v_lshl_add_u32 v1, v1, 3, s4
	s_waitcnt lgkmcnt(0)
	v_readfirstlane_b32 s1, v5
	v_readfirstlane_b32 s0, v4
	ds_read_b64 v[4:5], v1
	v_mov_b32_e32 v1, 8
	s_waitcnt lgkmcnt(0)
	v_readfirstlane_b32 s2, v5
	v_lshl_add_u32 v1, v1, 3, s4
	v_readfirstlane_b32 s3, v4
	ds_read_b64 v[4:5], v1
	v_mov_b32_e32 v1, v0
	s_waitcnt lgkmcnt(0)
	v_readfirstlane_b32 s4, v5
	v_ashrrev_i32_e32 v2, 6, v1
	v_add_u32_e32 v42, s75, v2
	v_readfirstlane_b32 s5, v4
	v_cmp_gt_i32_e32 vcc, s92, v42
	s_and_saveexec_b64 s[10:11], vcc
	s_cbranch_execz .LBB0_1316
	s_add_u32 s12, s0, 0xe400000
	s_addc_u32 s13, s1, 0
	s_lshl_b64 s[6:7], s[64:65], 2
	s_add_u32 s8, s3, s6
	v_lshlrev_b32_e32 v1, 3, v1
	s_addc_u32 s9, s2, s7
	v_and_b32_e32 v32, 0x1f8, v1
	s_add_u32 s2, s5, s6
	v_lshlrev_b32_e32 v1, 2, v32
	s_addc_u32 s3, s4, s7
	global_load_dwordx4 v[4:7], v1, s[8:9] offset:16
	global_load_dwordx4 v[8:11], v1, s[8:9]
	global_load_dwordx4 v[12:15], v1, s[2:3] offset:16
	global_load_dwordx4 v[16:19], v1, s[2:3]
	v_lshlrev_b32_e32 v2, 1, v32
	v_lshl_add_u64 v[20:21], s[0:1], 0, v[2:3]
	s_mov_b64 s[0:1], 0x3bc00000
	v_lshl_add_u64 v[34:35], v[20:21], 0, s[0:1]
	s_mov_b64 s[14:15], 0
	s_waitcnt vmcnt(0)
	s_branch .LBB0_1310

; __device__ __forceinline__ float bf2f(bf16 v) { return __uint_as_float(((unsigned)v) << 16); }
; __device__ __forceinline__ float gelu_tanh(float x) { const float u = 1.5957691216057308f * (x + 0.044715f * x * x * x); return x * __builtin_amdgcn_rcpf(1.0f + __expf(-u)); }
; __device__ __forceinline__ void ph_sgu_prep(const bf16* __restrict__ proj, const float* __restrict__ ln_g, const float* __restrict__ ln_b, bf16* __restrict__ VLN) {
;     ...
;     for (int m0 = gw; m0 < M; m0 += 4 * ngw) {
;         u32x4 raw4[4];
; #pragma unroll
;         for (int k = 0; k < 4; ++k) { const int m = m0 + k * ngw < M ? m0 + k * ngw : m0; raw4[k] = *(const u32x4*)(proj + (size_t)m * NPROJ + PC_VB + lane * 8); }
; #pragma unroll
;         for (int k = 0; k < 4; ++k) { const int m = m0 + k * ngw;
;             if (m < M) {
;                 float v[8]; const unsigned rw[4] = {raw4[k].x, raw4[k].y, raw4[k].z, raw4[k].w};
;                 float s = 0.f;
; #pragma unroll
;                 for (int j = 0; j < 4; ++j) { v[2 * j] = gelu_tanh(bf2f((bf16)(rw[j] & 0xffff))); v[2 * j + 1] = gelu_tanh(bf2f((bf16)(rw[j] >> 16))); s += v[2 * j] + v[2 * j + 1]; }
;                 const float mu = wave_sum(s) * (1.f / 512.f); float q = 0.f;
; #pragma unroll
;                 for (int j = 0; j < 8; ++j) { v[j] -= mu; q += v[j] * v[j]; }
;                 const float rstd = rsqrtf(wave_sum(q) * (1.f / 512.f) + NORM_EPS);
.LBB0_1310:
	v_readlane_b32 s0, v254, 32
	v_mov_b64_e32 v[20:21], s[12:13]
	v_lshlrev_b32_e32 v2, 1, v32
	v_add_u32_e32 v38, s0, v42
	v_cmp_gt_i32_e64 s[6:7], s92, v38
	s_nop 1
	v_cndmask_b32_e64 v1, v42, v38, s[6:7]
	v_mad_i64_i32 v[22:23], s[0:1], v1, s23, v[20:21]
	s_mul_i32 s0, s33, 24
	s_nop 0
	v_add_u32_e32 v36, s0, v42
	v_cmp_gt_i32_e64 s[4:5], s92, v36
	v_lshl_add_u64 v[22:23], v[22:23], 0, v[2:3]
	v_add_co_u32_e32 v22, vcc, 0x1000, v22
	v_cndmask_b32_e64 v1, v42, v36, s[4:5]
	v_mad_i64_i32 v[24:25], s[0:1], v1, s23, v[20:21]
	v_lshl_add_u64 v[24:25], v[24:25], 0, v[2:3]
	v_mad_i64_i32 v[20:21], s[2:3], v42, s23, v[20:21]
	s_mov_b64 s[0:1], vcc
	v_add_co_u32_e32 v40, vcc, 0x1000, v24
	v_lshl_add_u64 v[20:21], v[20:21], 0, v[2:3]
	s_mov_b64 s[8:9], vcc
	v_add_co_u32_e32 v20, vcc, 0x1000, v20
	s_nop 1
	v_addc_co_u32_e32 v21, vcc, 0, v21, vcc
	global_load_dwordx4 v[28:31], v[20:21], off offset:3072
	v_addc_co_u32_e64 v23, vcc, 0, v23, s[0:1]
	v_addc_co_u32_e64 v41, vcc, 0, v25, s[8:9]
	global_load_dwordx4 v[24:27], v[22:23], off offset:3072
	s_nop 0
	global_load_dwordx4 v[20:23], v[40:41], off offset:3072
	s_add_u32 s94, s12, 0x1000
	s_addc_u32 s95, s13, 0
	v_add_u32_e32 v154, s28, v42
	v_cmp_gt_i32_e64 s[98:99], s92, v154
	v_mov_b64_e32 v[152:153], s[94:95]
	s_nop 0
	v_cndmask_b32_e64 v154, v42, v154, s[98:99]
	v_mad_i64_i32 v[152:153], s[100:101], v154, s23, v[152:153]
	v_lshl_add_u64 v[152:153], v[152:153], 0, v[2:3]
	global_load_dwordx4 v[148:151], v[152:153], off offset:3072
	s_waitcnt vmcnt(3)
	v_lshlrev_b32_e32 v44, 16, v30
	v_and_b32_e32 v45, 0xffff0000, v30
	v_lshlrev_b32_e32 v30, 16, v29
	v_lshlrev_b32_e32 v40, 16, v31
	v_mul_f32_e32 v49, 0x3d372713, v30
	v_and_b32_e32 v41, 0xffff0000, v31
	v_and_b32_e32 v31, 0xffff0000, v29
	v_mul_f32_e32 v1, 0x3d372713, v40
	v_mul_f32_e32 v37, 0x3d372713, v44
	v_mov_b32_e32 v50, v30
	v_mul_f32_e32 v49, v49, v30
	v_lshlrev_b32_e32 v46, 16, v28
	v_and_b32_e32 v47, 0xffff0000, v28
	v_mov_b32_e32 v28, v40
	v_mul_f32_e32 v29, 0x3d372713, v41
	v_mov_b32_e32 v39, v44
	v_mul_f32_e32 v43, 0x3d372713, v45
	v_mul_f32_e32 v51, 0x3d372713, v31
	v_mul_f32_e32 v1, v1, v40
	v_mul_f32_e32 v37, v37, v44
	v_fmac_f32_e32 v50, v49, v50
	v_mov_b32_e32 v33, v41
	v_mov_b32_e32 v48, v45
	v_mov_b32_e32 v52, v31
	v_mul_f32_e32 v29, v29, v41
	v_mul_f32_e32 v43, v43, v45
	v_mul_f32_e32 v51, v51, v31
	v_fmac_f32_e32 v28, v1, v28
	v_fmac_f32_e32 v39, v37, v39
	v_mul_f32_e32 v37, 0xbfcc422a, v50
	v_fmac_f32_e32 v33, v29, v33
	v_fmac_f32_e32 v48, v43, v48
	v_fmac_f32_e32 v52, v51, v52
	v_mul_f32_e32 v1, 0xbfcc422a, v28
	v_mul_f32_e32 v37, 0x3fb8aa3b, v37
	v_mul_f32_e32 v28, 0xbfcc422a, v33
	v_mul_f32_e32 v29, 0xbfcc422a, v39
	v_mul_f32_e32 v33, 0xbfcc422a, v48
	v_mul_f32_e32 v39, 0xbfcc422a, v52
	v_mul_f32_e32 v1, 0x3fb8aa3b, v1
	v_exp_f32_e32 v37, v37
	v_mul_f32_e32 v28, 0x3fb8aa3b, v28
	v_mul_f32_e32 v33, 0x3fb8aa3b, v33
	v_mul_f32_e32 v39, 0x3fb8aa3b, v39
	v_exp_f32_e32 v1, v1
	v_exp_f32_e32 v28, v28
	v_exp_f32_e32 v33, v33
	v_exp_f32_e32 v39, v39
	v_mul_f32_e32 v53, 0x3d372713, v46
	v_add_f32_e32 v37, 1.0, v37
	v_mov_b32_e32 v58, v46
	v_mul_f32_e32 v53, v53, v46
	v_add_f32_e32 v1, 1.0, v1
	v_rcp_f32_e32 v50, v37
	v_mul_f32_e32 v37, 0x3d372713, v47
	v_fmac_f32_e32 v58, v53, v58
	v_add_f32_e32 v43, 1.0, v28
	v_add_f32_e32 v33, 1.0, v33
	v_rcp_f32_e32 v28, v1
	v_add_f32_e32 v1, 1.0, v39
	v_mul_f32_e32 v37, v37, v47
	v_mov_b32_e32 v39, v47
	v_mul_f32_e32 v29, 0x3fb8aa3b, v29
	v_rcp_f32_e32 v49, v33
	v_mul_f32_e32 v33, 0xbfcc422a, v58
	v_fmac_f32_e32 v39, v37, v39
	v_exp_f32_e32 v29, v29
	v_mul_f32_e32 v33, 0x3fb8aa3b, v33
	v_mul_f32_e32 v37, 0xbfcc422a, v39
	v_exp_f32_e32 v33, v33
	v_mul_f32_e32 v37, 0x3fb8aa3b, v37
	v_exp_f32_e32 v37, v37
	v_add_f32_e32 v48, 1.0, v29
	v_rcp_f32_e32 v29, v43
	v_rcp_f32_e32 v48, v48
	v_rcp_f32_e32 v51, v1
	v_add_f32_e32 v1, 1.0, v33
	v_rcp_f32_e32 v58, v1
	v_add_f32_e32 v1, 1.0, v37
	v_rcp_f32_e32 v59, v1
	v_pk_mul_f32 v[52:53], v[28:29], v[40:41]
	v_pk_mul_f32 v[54:55], v[48:49], v[44:45]
	v_mov_b32_e32 v56, v53
	v_mov_b32_e32 v57, v55
	v_mov_b32_e32 v53, v54
	v_pk_add_f32 v[52:53], v[56:57], v[52:53]
	v_pk_mul_f32 v[54:55], v[50:51], v[30:31]
	v_pk_mul_f32 v[56:57], v[58:59], v[46:47]
	v_mov_b32_e32 v60, v55
	v_mov_b32_e32 v61, v57
	v_mov_b32_e32 v55, v56
	v_pk_add_f32 v[54:55], v[60:61], v[54:55]
	v_ashrrev_i32_e32 v43, 31, v42
	v_add_f32_e32 v1, 0, v55
	v_add_f32_e32 v1, v54, v1
	v_add_f32_e32 v1, v53, v1
	v_add_f32_e32 v1, v52, v1
	s_nop 1
	v_add_f32_dpp v1, v1, v1 row_ror:8 row_mask:0xf bank_mask:0xf bound_ctrl:1
	s_nop 1
	v_add_f32_dpp v1, v1, v1 row_ror:4 row_mask:0xf bank_mask:0xf bound_ctrl:1
	s_nop 1
	v_add_f32_dpp v1, v1, v1 row_ror:2 row_mask:0xf bank_mask:0xf bound_ctrl:1
	s_nop 1
	v_add_f32_dpp v1, v1, v1 row_ror:1 row_mask:0xf bank_mask:0xf bound_ctrl:1
	s_nop 0
	v_readlane_b32 s2, v1, 16
	v_readlane_b32 s3, v1, 48
	v_readlane_b32 s0, v1, 0
	v_readlane_b32 s1, v1, 32
	v_mov_b32_e32 v52, s2
	v_mov_b32_e32 v53, s3
	v_pk_add_f32 v[52:53], s[0:1], v[52:53]
	s_nop 0
	v_add_f32_e32 v1, v52, v53
	v_mul_f32_e32 v52, 0x3b000000, v1
	v_pk_fma_f32 v[46:47], v[58:59], v[46:47], v[52:53] op_sel_hi:[1,1,0] neg_lo:[0,0,1] neg_hi:[0,0,1]
	v_pk_fma_f32 v[30:31], v[50:51], v[30:31], v[52:53] op_sel_hi:[1,1,0] neg_lo:[0,0,1] neg_hi:[0,0,1]
	v_pk_mul_f32 v[54:55], v[46:47], v[46:47]
	v_pk_mul_f32 v[50:51], v[30:31], v[30:31]
	v_add_f32_e32 v1, v54, v55
	v_pk_fma_f32 v[44:45], v[48:49], v[44:45], v[52:53] op_sel_hi:[1,1,0] neg_lo:[0,0,1] neg_hi:[0,0,1]
	v_add_f32_e32 v1, v50, v1
	v_pk_mul_f32 v[48:49], v[44:45], v[44:45]
	v_add_f32_e32 v1, v51, v1
; __device__ __forceinline__ unsigned pk2(float lo, float hi) { f32x2 v = {lo, hi}; return __builtin_bit_cast(unsigned, __builtin_convertvector(v, bf16x2_hw)); }
; __device__ __forceinline__ void ph_sgu_prep(const bf16* __restrict__ proj, const float* __restrict__ ln_g, const float* __restrict__ ln_b, bf16* __restrict__ VLN) {
;     ...
;                 for (int j = 0; j < 8; ++j) { v[j] -= mu; q += v[j] * v[j]; }
;                 const float rstd = rsqrtf(wave_sum(q) * (1.f / 512.f) + NORM_EPS);
;                 u32x4 o; unsigned ow[4];
; #pragma unroll
;                 for (int j = 0; j < 4; ++j) ow[j] = pk2(v[2 * j] * rstd * lg[2 * j] + lb[2 * j], v[2 * j + 1] * rstd * lg[2 * j + 1] + lb[2 * j + 1]);
;                 o.x = ow[0]; o.y = ow[1]; o.z = ow[2]; o.w = ow[3];
;                 *(u32x4*)(VLN + (size_t)m * 512 + lane * 8) = o;
;             } }
	v_pk_fma_f32 v[52:53], v[28:29], v[40:41], v[52:53] op_sel_hi:[1,1,0] neg_lo:[0,0,1] neg_hi:[0,0,1]
	v_add_f32_e32 v1, v48, v1
	v_pk_mul_f32 v[28:29], v[52:53], v[52:53]
	v_add_f32_e32 v1, v49, v1
	v_add_f32_e32 v1, v28, v1
	v_add_f32_e32 v1, v29, v1
	v_add_u32_e32 v40, s28, v42
	v_cmp_gt_i32_e32 vcc, s92, v40
	v_add_f32_dpp v1, v1, v1 row_ror:8 row_mask:0xf bank_mask:0xf bound_ctrl:1
	s_nop 1
	v_add_f32_dpp v1, v1, v1 row_ror:4 row_mask:0xf bank_mask:0xf bound_ctrl:1
	s_nop 1
	v_add_f32_dpp v1, v1, v1 row_ror:2 row_mask:0xf bank_mask:0xf bound_ctrl:1
	s_nop 1
	v_add_f32_dpp v1, v1, v1 row_ror:1 row_mask:0xf bank_mask:0xf bound_ctrl:1
	s_nop 0
	v_readlane_b32 s2, v1, 16
	v_readlane_b32 s3, v1, 48
	v_readlane_b32 s0, v1, 0
	v_readlane_b32 s1, v1, 32
	v_mov_b32_e32 v28, s2
	v_mov_b32_e32 v29, s3
	v_pk_add_f32 v[28:29], s[0:1], v[28:29]
	s_nop 0
	v_add_f32_e32 v1, v28, v29
	v_fmamk_f32 v1, v1, 0x3b000000, v232
	v_mul_f32_e32 v28, 0x4b800000, v1
	v_cmp_gt_f32_e64 s[0:1], s22, v1
	s_nop 1
	v_cndmask_b32_e64 v1, v1, v28, s[0:1]
	v_rsq_f32_e32 v1, v1
	s_nop 0
	v_mul_f32_e32 v28, 0x45800000, v1
	v_cndmask_b32_e64 v48, v1, v28, s[0:1]
	v_pk_mul_f32 v[28:29], v[46:47], v[48:49] op_sel_hi:[1,0]
	v_pk_mul_f32 v[30:31], v[30:31], v[48:49] op_sel_hi:[1,0]
	v_pk_fma_f32 v[28:29], v[8:9], v[28:29], v[16:17]
	v_pk_fma_f32 v[30:31], v[10:11], v[30:31], v[18:19]
	v_cvt_pk_bf16_f32 v28, v28, v29
	v_cvt_pk_bf16_f32 v29, v30, v31
	v_pk_mul_f32 v[30:31], v[44:45], v[48:49] op_sel_hi:[1,0]
	v_pk_mul_f32 v[44:45], v[52:53], v[48:49] op_sel_hi:[1,0]
	v_pk_fma_f32 v[30:31], v[4:5], v[30:31], v[12:13]
	v_pk_fma_f32 v[44:45], v[6:7], v[44:45], v[14:15]
	v_cvt_pk_bf16_f32 v30, v30, v31
	v_cvt_pk_bf16_f32 v31, v44, v45
	v_lshlrev_b64 v[44:45], 10, v[42:43]
	v_lshl_add_u64 v[44:45], v[34:35], 0, v[44:45]
	global_store_dwordx4 v[44:45], v[28:31], off
	s_and_saveexec_b64 s[0:1], vcc
	s_cbranch_execz .LBB0_1313
; __device__ __forceinline__ float bf2f(bf16 v) { return __uint_as_float(((unsigned)v) << 16); }
; __device__ __forceinline__ unsigned pk2(float lo, float hi) { f32x2 v = {lo, hi}; return __builtin_bit_cast(unsigned, __builtin_convertvector(v, bf16x2_hw)); }
; __device__ __forceinline__ float gelu_tanh(float x) { const float u = 1.5957691216057308f * (x + 0.044715f * x * x * x); return x * __builtin_amdgcn_rcpf(1.0f + __expf(-u)); }
; __device__ __forceinline__ void ph_sgu_prep(const bf16* __restrict__ proj, const float* __restrict__ ln_g, const float* __restrict__ ln_b, bf16* __restrict__ VLN) {
;     ...
;         for (int k = 0; k < 4; ++k) { const int m = m0 + k * ngw;
;             if (m < M) {
;                 float v[8]; const unsigned rw[4] = {raw4[k].x, raw4[k].y, raw4[k].z, raw4[k].w};
;                 float s = 0.f;
; #pragma unroll
;                 for (int j = 0; j < 4; ++j) { v[2 * j] = gelu_tanh(bf2f((bf16)(rw[j] & 0xffff))); v[2 * j + 1] = gelu_tanh(bf2f((bf16)(rw[j] >> 16))); s += v[2 * j] + v[2 * j + 1]; }
;                 const float mu = wave_sum(s) * (1.f / 512.f); float q = 0.f;
; #pragma unroll
;                 for (int j = 0; j < 8; ++j) { v[j] -= mu; q += v[j] * v[j]; }
;                 const float rstd = rsqrtf(wave_sum(q) * (1.f / 512.f) + NORM_EPS);
;                 u32x4 o; unsigned ow[4];
; #pragma unroll
;                 for (int j = 0; j < 4; ++j) ow[j] = pk2(v[2 * j] * rstd * lg[2 * j] + lb[2 * j], v[2 * j + 1] * rstd * lg[2 * j + 1] + lb[2 * j + 1]);
;                 o.x = ow[0]; o.y = ow[1]; o.z = ow[2]; o.w = ow[3];
;                 *(u32x4*)(VLN + (size_t)m * 512 + lane * 8) = o;
;             } }
	v_ashrrev_i32_e32 v41, 31, v40
	s_waitcnt vmcnt(1)
	v_mov_b32_e32 v28, v148
	v_mov_b32_e32 v29, v149
	v_mov_b32_e32 v30, v150
	v_mov_b32_e32 v31, v151
	v_lshlrev_b32_e32 v42, 16, v31
	v_mul_f32_e32 v1, 0x3d372713, v42
	v_mul_f32_e32 v1, v1, v42
	v_mov_b32_e32 v2, v42
	v_fmac_f32_e32 v2, v1, v2
	v_mul_f32_e32 v1, 0xbfcc422a, v2
	v_mul_f32_e32 v1, 0x3fb8aa3b, v1
	v_exp_f32_e32 v1, v1
	v_and_b32_e32 v43, 0xffff0000, v31
	v_mov_b32_e32 v2, v43
	v_lshlrev_b32_e32 v46, 16, v30
	v_add_f32_e32 v1, 1.0, v1
	v_rcp_f32_e32 v44, v1
	v_mul_f32_e32 v1, 0x3d372713, v43
	v_mul_f32_e32 v1, v1, v43
	v_fmac_f32_e32 v2, v1, v2
	v_mul_f32_e32 v1, 0xbfcc422a, v2
	v_mul_f32_e32 v1, 0x3fb8aa3b, v1
	v_exp_f32_e32 v1, v1
	v_mov_b32_e32 v2, v46
	v_and_b32_e32 v47, 0xffff0000, v30
	v_lshlrev_b32_e32 v56, 16, v28
	v_add_f32_e32 v1, 1.0, v1
	v_rcp_f32_e32 v45, v1
	v_mul_f32_e32 v1, 0x3d372713, v46
	v_mul_f32_e32 v1, v1, v46
	v_fmac_f32_e32 v2, v1, v2
	v_mul_f32_e32 v1, 0xbfcc422a, v2
	v_mul_f32_e32 v1, 0x3fb8aa3b, v1
	v_exp_f32_e32 v1, v1
	v_mov_b32_e32 v2, v47
	v_pk_mul_f32 v[48:49], v[44:45], v[42:43]
	v_and_b32_e32 v57, 0xffff0000, v28
	v_add_f32_e32 v1, 1.0, v1
	v_rcp_f32_e32 v30, v1
	v_mul_f32_e32 v1, 0x3d372713, v47
	v_mul_f32_e32 v1, v1, v47
	v_fmac_f32_e32 v2, v1, v2
	v_mul_f32_e32 v1, 0xbfcc422a, v2
	v_mul_f32_e32 v1, 0x3fb8aa3b, v1
	v_exp_f32_e32 v1, v1
	v_mov_b32_e32 v52, v49
	v_add_f32_e32 v1, 1.0, v1
	v_rcp_f32_e32 v31, v1
	s_nop 0
	v_pk_mul_f32 v[50:51], v[30:31], v[46:47]
	s_nop 0
	v_mov_b32_e32 v49, v50
	v_lshlrev_b32_e32 v50, 16, v29
	v_mul_f32_e32 v1, 0x3d372713, v50
	v_mul_f32_e32 v1, v1, v50
	v_mov_b32_e32 v2, v50
	v_fmac_f32_e32 v2, v1, v2
	v_mul_f32_e32 v1, 0xbfcc422a, v2
	v_mul_f32_e32 v1, 0x3fb8aa3b, v1
	v_exp_f32_e32 v1, v1
	v_mov_b32_e32 v53, v51
	v_and_b32_e32 v51, 0xffff0000, v29
	v_pk_add_f32 v[48:49], v[52:53], v[48:49]
	v_add_f32_e32 v1, 1.0, v1
	v_rcp_f32_e32 v52, v1
	v_mul_f32_e32 v1, 0x3d372713, v51
	v_mul_f32_e32 v1, v1, v51
	v_mov_b32_e32 v2, v51
	v_fmac_f32_e32 v2, v1, v2
	v_mul_f32_e32 v1, 0xbfcc422a, v2
	v_mul_f32_e32 v1, 0x3fb8aa3b, v1
	v_exp_f32_e32 v1, v1
	v_mov_b32_e32 v2, v56
	v_add_f32_e32 v1, 1.0, v1
	v_rcp_f32_e32 v53, v1
	v_mul_f32_e32 v1, 0x3d372713, v56
	v_mul_f32_e32 v1, v1, v56
	v_fmac_f32_e32 v2, v1, v2
	v_mul_f32_e32 v1, 0xbfcc422a, v2
	v_mul_f32_e32 v1, 0x3fb8aa3b, v1
	v_exp_f32_e32 v1, v1
	v_mov_b32_e32 v2, v57
	v_pk_mul_f32 v[54:55], v[52:53], v[50:51]
	v_add_f32_e32 v1, 1.0, v1
	v_rcp_f32_e32 v28, v1
	v_mul_f32_e32 v1, 0x3d372713, v57
	v_mul_f32_e32 v1, v1, v57
	v_fmac_f32_e32 v2, v1, v2
	v_mul_f32_e32 v1, 0xbfcc422a, v2
	v_mul_f32_e32 v1, 0x3fb8aa3b, v1
	v_exp_f32_e32 v1, v1
	v_mov_b32_e32 v60, v55
	v_add_f32_e32 v1, 1.0, v1
	v_rcp_f32_e32 v29, v1
	s_nop 0
	v_pk_mul_f32 v[58:59], v[28:29], v[56:57]
	s_nop 0
	v_mov_b32_e32 v61, v59
	v_mov_b32_e32 v55, v58
	v_pk_add_f32 v[54:55], v[60:61], v[54:55]
	s_nop 0
	v_add_f32_e32 v1, 0, v55
	v_add_f32_e32 v1, v54, v1
	v_add_f32_e32 v1, v49, v1
	v_add_f32_e32 v1, v48, v1
	s_nop 1
	v_add_f32_dpp v1, v1, v1 row_ror:8 row_mask:0xf bank_mask:0xf bound_ctrl:1
	s_nop 1
	v_add_f32_dpp v1, v1, v1 row_ror:4 row_mask:0xf bank_mask:0xf bound_ctrl:1
	s_nop 1
	v_add_f32_dpp v1, v1, v1 row_ror:2 row_mask:0xf bank_mask:0xf bound_ctrl:1
	s_nop 1
	v_add_f32_dpp v1, v1, v1 row_ror:1 row_mask:0xf bank_mask:0xf bound_ctrl:1
	s_nop 0
	v_readlane_b32 s8, v1, 16
	v_readlane_b32 s9, v1, 48
	v_readlane_b32 s2, v1, 0
	v_readlane_b32 s3, v1, 32
	v_mov_b32_e32 v48, s8
	v_mov_b32_e32 v49, s9
	v_pk_add_f32 v[48:49], s[2:3], v[48:49]
	s_nop 0
	v_add_f32_e32 v1, v48, v49
	v_mul_f32_e32 v2, 0x3b000000, v1
	v_pk_fma_f32 v[28:29], v[28:29], v[56:57], v[2:3] op_sel_hi:[1,1,0] neg_lo:[0,0,1] neg_hi:[0,0,1]
	v_pk_fma_f32 v[50:51], v[52:53], v[50:51], v[2:3] op_sel_hi:[1,1,0] neg_lo:[0,0,1] neg_hi:[0,0,1]
	v_pk_mul_f32 v[48:49], v[28:29], v[28:29]
	v_pk_mul_f32 v[52:53], v[50:51], v[50:51]
	v_add_f32_e32 v1, v48, v49
	v_pk_fma_f32 v[30:31], v[30:31], v[46:47], v[2:3] op_sel_hi:[1,1,0] neg_lo:[0,0,1] neg_hi:[0,0,1]
	v_add_f32_e32 v1, v52, v1
	v_pk_mul_f32 v[46:47], v[30:31], v[30:31]
	v_add_f32_e32 v1, v53, v1
	v_pk_fma_f32 v[42:43], v[44:45], v[42:43], v[2:3] op_sel_hi:[1,1,0] neg_lo:[0,0,1] neg_hi:[0,0,1]
	v_add_f32_e32 v1, v46, v1
	v_pk_mul_f32 v[44:45], v[42:43], v[42:43]
	v_add_f32_e32 v1, v47, v1
	v_add_f32_e32 v1, v44, v1
	v_add_f32_e32 v1, v45, v1
	s_nop 1
	v_add_f32_dpp v1, v1, v1 row_ror:8 row_mask:0xf bank_mask:0xf bound_ctrl:1
	s_nop 1
	v_add_f32_dpp v1, v1, v1 row_ror:4 row_mask:0xf bank_mask:0xf bound_ctrl:1
	s_nop 1
	v_add_f32_dpp v1, v1, v1 row_ror:2 row_mask:0xf bank_mask:0xf bound_ctrl:1
	s_nop 1
	v_add_f32_dpp v1, v1, v1 row_ror:1 row_mask:0xf bank_mask:0xf bound_ctrl:1
	s_nop 0
	v_readlane_b32 s8, v1, 16
	v_readlane_b32 s9, v1, 48
	v_readlane_b32 s2, v1, 0
	v_readlane_b32 s3, v1, 32
	v_mov_b32_e32 v44, s8
	v_mov_b32_e32 v45, s9
	v_pk_add_f32 v[44:45], s[2:3], v[44:45]
	s_nop 0
	v_add_f32_e32 v1, v44, v45
	v_fmamk_f32 v1, v1, 0x3b000000, v232
	v_cmp_gt_f32_e32 vcc, s22, v1
	v_mul_f32_e32 v2, 0x4b800000, v1
	s_nop 0
	v_cndmask_b32_e32 v1, v1, v2, vcc
	v_rsq_f32_e32 v1, v1
	s_nop 0
	v_mul_f32_e32 v2, 0x45800000, v1
	v_cndmask_b32_e32 v2, v1, v2, vcc
	v_pk_mul_f32 v[30:31], v[30:31], v[2:3] op_sel_hi:[1,0]
	v_pk_mul_f32 v[42:43], v[42:43], v[2:3] op_sel_hi:[1,0]
	v_pk_mul_f32 v[28:29], v[28:29], v[2:3] op_sel_hi:[1,0]
	v_pk_mul_f32 v[44:45], v[50:51], v[2:3] op_sel_hi:[1,0]
	v_pk_fma_f32 v[30:31], v[4:5], v[30:31], v[12:13]
	v_pk_fma_f32 v[42:43], v[6:7], v[42:43], v[14:15]
	v_pk_fma_f32 v[28:29], v[8:9], v[28:29], v[16:17]
	v_pk_fma_f32 v[44:45], v[10:11], v[44:45], v[18:19]
	v_cvt_pk_bf16_f32 v30, v30, v31
	v_cvt_pk_bf16_f32 v31, v42, v43
	v_lshlrev_b64 v[42:43], 10, v[40:41]
	v_cvt_pk_bf16_f32 v28, v28, v29
	v_cvt_pk_bf16_f32 v29, v44, v45
	v_lshl_add_u64 v[42:43], v[34:35], 0, v[42:43]
	global_store_dwordx4 v[42:43], v[28:31], off
	s_or_b64 exec, exec, s[0:1]
	s_and_saveexec_b64 s[0:1], s[6:7]
	s_cbranch_execnz .LBB0_1314

; __device__ __forceinline__ int ltid() { int t = threadIdx.x; asm volatile("" : "+v"(t)); return t; }
; __device__ __forceinline__ void ph_nsa_prep2(const bf16* __restrict__ proj, const float* __restrict__ qg, const float* __restrict__ kg, bf16* __restrict__ NQ, bf16* __restrict__ KS, bf16* __restrict__ KW,
;                                              bf16* __restrict__ VST, bf16* __restrict__ VWT) {
;     const int tid = ltid(); const int lane = tid & 63; const int gw = blockIdx.x * NWAVES + (tid >> 6), ngw = gridDim.x * NWAVES;
;     {
;         const int c0 = (lane & 15) * 8;
;         const f32x4 qg0 = *(const f32x4*)(qg + c0), qg1 = *(const f32x4*)(qg + c0 + 4), kg0 = *(const f32x4*)(kg + c0), kg1 = *(const f32x4*)(kg + c0 + 4);
;         const int pstep = ngw * 4;
;         for (int p0 = gw * 4 + (lane >> 4); p0 < M * 10; p0 += 4 * pstep) {
.LBB0_1316:
	s_or_b64 exec, exec, s[10:11]
	v_mov_b32_e32 v1, 22
	v_readlane_b32 s2, v254, 35
	v_mov_b32_e32 v39, v0
	s_nop 0
	v_lshl_add_u32 v1, v1, 3, s2
	ds_read_b64 v[4:5], v1
	v_mov_b32_e32 v1, 11
	s_waitcnt lgkmcnt(0)
	v_readfirstlane_b32 s13, v5
	v_lshl_add_u32 v1, v1, 3, s2
	v_readfirstlane_b32 s12, v4
	ds_read_b64 v[4:5], v1
	v_mov_b32_e32 v1, 12
	s_add_u32 s14, s12, 0xe400000
	v_lshl_add_u32 v1, v1, 3, s2
	s_waitcnt lgkmcnt(0)
	v_readfirstlane_b32 s0, v5
	v_readfirstlane_b32 s1, v4
	ds_read_b64 v[4:5], v1
	s_addc_u32 s15, s13, 0
	v_ashrrev_i32_e32 v37, 6, v39
	v_add_u32_e32 v68, s75, v37
	v_bfe_u32 v1, v39, 4, 2
	v_lshl_or_b32 v36, v68, 2, v1
	s_waitcnt lgkmcnt(0)
	v_readfirstlane_b32 s2, v5
	v_readfirstlane_b32 s3, v4
	v_cmp_gt_i32_e32 vcc, s69, v36
	s_and_saveexec_b64 s[16:17], vcc
	s_cbranch_execz .LBB0_1389
	v_readlane_b32 s4, v255, 4
	v_readlane_b32 s5, v255, 5
	s_lshl_b64 s[4:5], s[4:5], 2
	s_add_u32 s6, s1, s4
	v_lshlrev_b32_e32 v1, 3, v39
	s_addc_u32 s7, s0, s5
	v_and_b32_e32 v2, 0x78, v1
	s_add_u32 s0, s3, s4
	v_lshlrev_b32_e32 v1, 2, v2
	s_addc_u32 s1, s2, s5
	global_load_dwordx4 v[4:7], v1, s[6:7] offset:16
	global_load_dwordx4 v[8:11], v1, s[6:7]
	global_load_dwordx4 v[12:15], v1, s[0:1] offset:16
	global_load_dwordx4 v[16:19], v1, s[0:1]
	s_add_u32 s20, s12, 0x28800000
	s_addc_u32 s21, s13, 0
	s_add_u32 s34, s12, 0x2b800000
	s_addc_u32 s35, s13, 0
	s_add_u32 s36, s12, 0x2c800000
	v_readlane_b32 s0, v254, 13
	s_addc_u32 s37, s13, 0
	v_lshlrev_b32_e32 v38, 7, v36
	s_lshl_b32 s2, s0, 7
	s_mov_b64 s[38:39], 0
	v_lshlrev_b32_e32 v40, 1, v2
	s_waitcnt vmcnt(0)
	s_branch .LBB0_1320

; __device__ __forceinline__ void ph_nsa_prep2(const bf16* __restrict__ proj, const float* __restrict__ qg, const float* __restrict__ kg, bf16* __restrict__ NQ, bf16* __restrict__ KS, bf16* __restrict__ KW,
;                                              bf16* __restrict__ VST, bf16* __restrict__ VWT) {
;     ...
;         for (int p0 = gw * 4 + (lane >> 4); p0 < M * 10; p0 += 4 * pstep) {
;             u32x4 prr[4];
; #pragma unroll
;             for (int k = 0; k < 4; ++k) { const int p = p0 + k * pstep; const int pc = p < M * 10 ? p : p0; const int m = pc / 10, j = pc % 10;
;                 const int src = j < 6 ? PC_QC + j * 128 : (j < 8 ? PC_KSL + (j - 6) * 128 : PC_KWN + (j - 8) * 128);
;                 prr[k] = *(const u32x4*)(proj + (size_t)m * NPROJ + src + c0); }
.LBB0_1326:
	s_andn2_saveexec_b64 s[0:1], s[0:1]
	s_movk_i32 s3, 0xfb00
	v_mul_lo_u32 v1, v45, s3
	v_add3_u32 v2, v38, v1, s79
	s_or_b64 exec, exec, s[0:1]
	v_mov_b64_e32 v[20:21], s[14:15]
	v_mad_i64_i32 v[20:21], s[0:1], v45, s23, v[20:21]
	v_lshl_add_u64 v[20:21], v[2:3], 1, v[20:21]
	v_mov_b32_e32 v41, v3
	v_lshl_add_u64 v[20:21], v[20:21], 0, v[40:41]
	global_load_dwordx4 v[32:35], v[20:21], off
	v_readlane_b32 s0, v254, 12
	s_nop 1
	v_add_u32_e32 v43, s0, v36
	v_cmp_gt_i32_e64 s[8:9], s69, v43
	s_nop 1
	v_cndmask_b32_e64 v2, v36, v43, s[8:9]
	v_mul_hi_i32 v1, v2, s70
	v_lshrrev_b32_e32 v20, 31, v1
	v_ashrrev_i32_e32 v1, 2, v1
	v_add_u32_e32 v1, v1, v20
	v_mul_lo_u32 v20, v1, 10
	v_sub_u32_e32 v20, v2, v20
	v_cmp_lt_i32_e32 vcc, 5, v20
	s_and_saveexec_b64 s[0:1], vcc
	s_xor_b64 s[0:1], exec, s[0:1]
	s_cbranch_execz .LBB0_1334
	v_cmp_lt_u32_e32 vcc, 7, v20
	v_lshlrev_b32_e32 v20, 7, v20
	s_and_saveexec_b64 s[4:5], vcc
	s_xor_b64 s[4:5], exec, s[4:5]
	v_add_u32_e32 v2, 0x1300, v20
	s_andn2_saveexec_b64 s[4:5], s[4:5]
	v_add_u32_e32 v2, 0x1200, v20
	s_or_b64 exec, exec, s[4:5]
